# in-proj: removed the entry block's register-staged K-step 0 (the first tile is always staged by the LDS-DMA restage)
# speedup vs baseline: 1.0039x; 1.0039x over previous
; DI int tidx() { int t = threadIdx.x; asm volatile("" : "+v"(t)); return t; }
; template <int EPI>
; DI void gemm_phase(const P& p, int l, const u16* __restrict__ A, const u16* __restrict__ Bt, int mpx, char* lds) {
;   const int tid = tidx();
;   int t = 0;
;   int m0, n0;
;   if (!tile_coords<EPI>(t, mpx, m0, n0)) return;
;   const unsigned voffb = (unsigned)(((tid >> 3) * 1024 + (tid & 7) * 8) * 2);
;   const u16* Ag = A + (size_t)m0 * 1024;
;   const u16* Bg = Bt + (size_t)n0 * 1024;
;   uint4 ra0, ra1, ra2, ra3, rb0, rb1, rb2, rb3;
;     ...
;   GLOAD(Ag, Bg, 0)
;   u16* As0 = (u16*)lds;
;   u16* Bs0 = As0 + 256 * 64;
;   u16* As1 = Bs0 + 256 * 64;
;   u16* Bs1 = As1 + 256 * 64;
;   const int lw = (tid >> 3) * 64 + (((tid & 7) ^ ((tid >> 3) & 7)) * 8);
;   GSTORE(As0, Bs0)
.Ltile_fix_done:
	s_mul_i32 s1, s50, 0x780000
	s_mul_hi_i32 s0, s50, 0x780000
	s_add_u32 s24, s12, s1
	s_addc_u32 s25, s13, s0
	s_lshl_b32 s52, s50, 6
	s_ashr_i32 s53, s52, 31
	v_lshlrev_b32_e32 v2, 4, v0
	v_readlane_b32 s0, v254, 60
	v_ashrrev_i32_e32 v34, 3, v0
	v_and_b32_e32 v2, 0x70, v2
	s_add_u32 s0, s24, s0
	v_lshl_or_b32 v196, v34, 11, v2
	s_addc_u32 s1, s25, 0
	v_mov_b32_e32 v197, v1
	v_readlane_b32 s26, v254, 61
	v_readlane_b32 s27, v254, 62
	v_lshl_add_u64 v[30:31], s[0:1], 0, v[196:197]
	v_readlane_b32 s42, v255, 1
	v_add_co_u32_e32 v22, vcc, s33, v30
	s_nop 0
	v_readlane_b32 s26, v254, 63
	v_readlane_b32 s43, v255, 2
	v_readlane_b32 s27, v255, 0
	v_addc_co_u32_e32 v23, vcc, 0, v31, vcc
	v_add_co_u32_e32 v26, vcc, s35, v30
	s_nop 1
	v_readlane_b32 s26, v255, 3
	v_readlane_b32 s27, v255, 4
	v_addc_co_u32_e32 v27, vcc, 0, v31, vcc
	v_add_co_u32_e32 v30, vcc, s39, v30
	v_lshrrev_b32_e32 v35, 4, v0
	s_nop 1
	s_nop 0
	s_nop 0
	v_addc_co_u32_e32 v31, vcc, 0, v31, vcc
	v_bfe_u32 v36, v0, 4, 2
	v_and_b32_e32 v37, 7, v0
	v_lshlrev_b32_e32 v38, 7, v0
	v_lshlrev_b32_e32 v39, 6, v0
	v_xor_b32_e32 v0, v34, v0
	v_bitop3_b32 v35, v35, v37, 3 bitop3:0x6c
	v_bitop3_b32 v36, v36, v37, 4 bitop3:0x36
	v_lshlrev_b32_e32 v0, 4, v0
	s_load_dword s2, s[76:77], 0x0
	v_and_b32_e32 v37, 0x6000, v38
	v_and_b32_e32 v39, 0xffffc000, v39
	v_lshlrev_b32_e32 v35, 4, v35
	v_lshlrev_b32_e32 v36, 4, v36
	v_and_b32_e32 v0, 0x70, v0
	v_readlane_b32 s40, v255, 23
	v_and_b32_e32 v38, 0x780, v38
	v_add_u32_e32 v40, 32, v35
	v_add_u32_e32 v41, 32, v36
	v_add3_u32 v42, s40, v35, v37
	v_add3_u32 v35, s78, v35, v39
	v_lshl_or_b32 v0, v34, 7, v0
	v_add3_u32 v43, s40, v36, v37
	v_add3_u32 v36, s78, v36, v39
	v_add_u32_e32 v34, v40, v37
	v_add_u32_e32 v40, v40, v39
	v_add_u32_e32 v37, v41, v37
	v_add_u32_e32 v39, v41, v39
	v_add_u32_e32 v198, v42, v38
	v_add_u32_e32 v199, v35, v38
	v_add_u32_e32 v35, 0x2000, v0
	v_add_u32_e32 v41, 0x4000, v0
	v_add_u32_e32 v42, 0x6000, v0
	v_add_u32_e32 v203, s40, v0
	v_add_u32_e32 v230, s40, v35
	v_add_u32_e32 v231, s40, v41
	v_add_u32_e32 v232, s40, v42
	v_readlane_b32 s40, v254, 58
	v_readlane_b32 s41, v254, 59
	s_mov_b32 s26, 0
	v_add_u32_e32 v200, v43, v38
	v_add_u32_e32 v201, 32, v0
	s_waitcnt lgkmcnt(0)
	s_lshr_b32 s27, s2, 3
	v_add_u32_e32 v202, s78, v0
	v_add_u32_e32 v204, v34, v38
	v_add_u32_e32 v205, v40, v38
	v_add_u32_e32 v206, v37, v38
	v_add_u32_e32 v207, v39, v38
	v_add_u32_e32 v227, s78, v35
	v_add_u32_e32 v228, s78, v41
	v_add_u32_e32 v229, s78, v42
	v_add_u32_e32 v233, v36, v38
	v_readlane_b32 s46, v254, 13
	s_mov_b32 s66, s40
	s_mov_b64 s[40:41], s[42:43]
	s_waitcnt vmcnt(5)
	s_waitcnt vmcnt(4)
	s_waitcnt vmcnt(3)
	s_waitcnt vmcnt(2)
	s_waitcnt vmcnt(1)
	s_waitcnt vmcnt(0)
	s_mov_b32 s101, 1
	s_branch .LBB0_79
